# strategy 7.4: one static s_setprio 1 for waves 4-7 (younger half), set once at kernel entry
# speedup vs baseline: 1.0045x; 1.0045x over previous
.LBB0_5:
	s_or_b64 exec, exec, s[4:5]
	v_readfirstlane_b32 s4, v137
	s_nop 3
	s_lshr_b32 s4, s4, 6
	s_cmp_ge_u32 s4, 4
	s_cbranch_scc0 .Lprio_done
	s_setprio 1
.Lprio_done:
	s_cmp_ge_i32 s80, s81
	s_cbranch_scc0 .LBB0_6
	s_getpc_b64 s[98:99]
